# GU SwiGLU epilogue rewritten (fold row scale into exp arg and denominator, packed fma; 41 vs 58 VALU per row block); MLA K/V loads use running per-lane pointers; decide-block canonicalizing maxes remo
# speedup vs baseline: 1.0061x; 1.0013x over previous
; __device__ __forceinline__ u32x4 pack8(const f32x4& a, const f32x4& b) { u32x4 w; w.x = cvt_pk_bf16(a[0], a[1]); w.y = cvt_pk_bf16(a[2], a[3]); w.z = cvt_pk_bf16(b[0], b[1]); w.w = cvt_pk_bf16(b[2], b[3]); return w; }
; __device__ __forceinline__ float silu_mul(float g, float u) { return g * u * __builtin_amdgcn_rcpf(1.f + __builtin_amdgcn_exp2f(-1.4426950408889634f * g)); }
;     __device__ __forceinline__ void operator()(const f32x4 (&acc)[2][2][4][2], const Unit& u, int wr, int wc, int fr, int fq) const {
;         const int row0 = u.pm * BM + wr * 64 + fr, col0 = u.pn * HALF + wc * 32 + 8 * fq;
; #pragma unroll
;         for (int ai = 0; ai < 2; ++ai)
; #pragma unroll
;             for (int m = 0; m < 4; ++m) { f32x4 r0, r1; const float r = rs[row0 + ai * HALF + m * 16];
; #pragma unroll
;                 for (int e = 0; e < 4; ++e) { r0[e] = silu_mul(acc[ai][0][m][0][e] * r, acc[ai][1][m][0][e] * r); r1[e] = silu_mul(acc[ai][0][m][1][e] * r, acc[ai][1][m][1][e] * r); }
;                 *(u32x4*)(O + (size_t)(row0 + ai * HALF + m * 16) * ldc + col0) = pack8(r0, r1); }
.LBB0_229:
	v_lshl_add_u32 v140, s63, 8, v146
	v_ashrrev_i32_e32 v141, 31, v140
	v_lshl_add_u64 v[142:143], v[140:141], 2, s[16:17]
	global_load_dword v150, v[142:143], off
	global_load_dword v154, v[142:143], off offset:64
	global_load_dword v155, v[142:143], off offset:128
	global_load_dword v156, v[142:143], off offset:192
	global_load_dword v157, v[142:143], off offset:512
	global_load_dword v158, v[142:143], off offset:576
	global_load_dword v159, v[142:143], off offset:640
	global_load_dword v160, v[142:143], off offset:704
	v_lshl_or_b32 v144, s1, 7, v148
	v_ashrrev_i32_e32 v145, 31, v144
	s_mov_b64 s[42:43], -1
	s_andn2_b64 vcc, exec, s[4:5]
	s_waitcnt vmcnt(0)
	v_mov_b64_e32 v[186:187], s[10:11]
	v_lshlrev_b64 v[188:189], 1, v[144:145]
	v_mad_i64_i32 v[186:187], s[0:1], v140, s51, v[186:187]
	v_lshl_add_u64 v[186:187], v[186:187], 0, v[188:189]
	s_mov_b32 s59, 0
	v_mul_f32_e32 v178, 0xbfb8aa3b, v150
	v_mul_f32_e32 v180, v150, v150
	v_rcp_f32_e32 v180, v180
	v_pk_mul_f32 v[170:171], v[126:127], v[178:179] op_sel_hi:[1,0]
	v_pk_mul_f32 v[172:173], v[128:129], v[178:179] op_sel_hi:[1,0]
	v_pk_mul_f32 v[174:175], v[122:123], v[178:179] op_sel_hi:[1,0]
	v_pk_mul_f32 v[176:177], v[124:125], v[178:179] op_sel_hi:[1,0]
	v_exp_f32_e32 v170, v170
	v_exp_f32_e32 v171, v171
	v_exp_f32_e32 v172, v172
	v_exp_f32_e32 v173, v173
	v_exp_f32_e32 v174, v174
	v_exp_f32_e32 v175, v175
	v_exp_f32_e32 v176, v176
	v_exp_f32_e32 v177, v177
	v_pk_fma_f32 v[170:171], v[170:171], v[180:181], v[180:181] op_sel_hi:[1,0,0]
	v_pk_fma_f32 v[172:173], v[172:173], v[180:181], v[180:181] op_sel_hi:[1,0,0]
	v_pk_fma_f32 v[174:175], v[174:175], v[180:181], v[180:181] op_sel_hi:[1,0,0]
	v_pk_fma_f32 v[176:177], v[176:177], v[180:181], v[180:181] op_sel_hi:[1,0,0]
	v_rcp_f32_e32 v170, v170
	v_rcp_f32_e32 v171, v171
	v_rcp_f32_e32 v172, v172
	v_rcp_f32_e32 v173, v173
	v_rcp_f32_e32 v174, v174
	v_rcp_f32_e32 v175, v175
	v_rcp_f32_e32 v176, v176
	v_rcp_f32_e32 v177, v177
	v_pk_mul_f32 v[118:119], v[126:127], v[118:119]
	v_pk_mul_f32 v[120:121], v[128:129], v[120:121]
	v_pk_mul_f32 v[114:115], v[122:123], v[114:115]
	v_pk_mul_f32 v[116:117], v[124:125], v[116:117]
	v_pk_mul_f32 v[118:119], v[118:119], v[170:171]
	v_pk_mul_f32 v[120:121], v[120:121], v[172:173]
	v_pk_mul_f32 v[114:115], v[114:115], v[174:175]
	v_pk_mul_f32 v[116:117], v[116:117], v[176:177]
	v_cvt_pk_bf16_f32 v182, v118, v119
	v_cvt_pk_bf16_f32 v183, v120, v121
	v_cvt_pk_bf16_f32 v184, v114, v115
	v_cvt_pk_bf16_f32 v185, v116, v117
	global_store_dwordx4 v[186:187], v[182:185], off
	s_mul_i32 s58, s51, 0x10
	v_lshl_add_u64 v[188:189], v[186:187], 0, s[58:59]
	v_mul_f32_e32 v178, 0xbfb8aa3b, v154
	v_mul_f32_e32 v180, v154, v154
	v_rcp_f32_e32 v180, v180
	v_pk_mul_f32 v[170:171], v[110:111], v[178:179] op_sel_hi:[1,0]
	v_pk_mul_f32 v[172:173], v[112:113], v[178:179] op_sel_hi:[1,0]
	v_pk_mul_f32 v[174:175], v[106:107], v[178:179] op_sel_hi:[1,0]
	v_pk_mul_f32 v[176:177], v[108:109], v[178:179] op_sel_hi:[1,0]
	v_exp_f32_e32 v170, v170
	v_exp_f32_e32 v171, v171
	v_exp_f32_e32 v172, v172
	v_exp_f32_e32 v173, v173
	v_exp_f32_e32 v174, v174
	v_exp_f32_e32 v175, v175
	v_exp_f32_e32 v176, v176
	v_exp_f32_e32 v177, v177
	v_pk_fma_f32 v[170:171], v[170:171], v[180:181], v[180:181] op_sel_hi:[1,0,0]
	v_pk_fma_f32 v[172:173], v[172:173], v[180:181], v[180:181] op_sel_hi:[1,0,0]
	v_pk_fma_f32 v[174:175], v[174:175], v[180:181], v[180:181] op_sel_hi:[1,0,0]
	v_pk_fma_f32 v[176:177], v[176:177], v[180:181], v[180:181] op_sel_hi:[1,0,0]
	v_rcp_f32_e32 v170, v170
	v_rcp_f32_e32 v171, v171
	v_rcp_f32_e32 v172, v172
	v_rcp_f32_e32 v173, v173
	v_rcp_f32_e32 v174, v174
	v_rcp_f32_e32 v175, v175
	v_rcp_f32_e32 v176, v176
	v_rcp_f32_e32 v177, v177
	v_pk_mul_f32 v[102:103], v[110:111], v[102:103]
	v_pk_mul_f32 v[104:105], v[112:113], v[104:105]
	v_pk_mul_f32 v[98:99], v[106:107], v[98:99]
	v_pk_mul_f32 v[100:101], v[108:109], v[100:101]
	v_pk_mul_f32 v[102:103], v[102:103], v[170:171]
	v_pk_mul_f32 v[104:105], v[104:105], v[172:173]
	v_pk_mul_f32 v[98:99], v[98:99], v[174:175]
	v_pk_mul_f32 v[100:101], v[100:101], v[176:177]
	v_cvt_pk_bf16_f32 v182, v102, v103
	v_cvt_pk_bf16_f32 v183, v104, v105
	v_cvt_pk_bf16_f32 v184, v98, v99
	v_cvt_pk_bf16_f32 v185, v100, v101
	global_store_dwordx4 v[188:189], v[182:185], off
	s_mul_i32 s58, s51, 0x10
	v_lshl_add_u64 v[186:187], v[188:189], 0, s[58:59]
	v_mul_f32_e32 v178, 0xbfb8aa3b, v155
	v_mul_f32_e32 v180, v155, v155
	v_rcp_f32_e32 v180, v180
	v_pk_mul_f32 v[170:171], v[94:95], v[178:179] op_sel_hi:[1,0]
	v_pk_mul_f32 v[172:173], v[96:97], v[178:179] op_sel_hi:[1,0]
	v_pk_mul_f32 v[174:175], v[90:91], v[178:179] op_sel_hi:[1,0]
	v_pk_mul_f32 v[176:177], v[92:93], v[178:179] op_sel_hi:[1,0]
	v_exp_f32_e32 v170, v170
	v_exp_f32_e32 v171, v171
	v_exp_f32_e32 v172, v172
	v_exp_f32_e32 v173, v173
	v_exp_f32_e32 v174, v174
	v_exp_f32_e32 v175, v175
	v_exp_f32_e32 v176, v176
	v_exp_f32_e32 v177, v177
	v_pk_fma_f32 v[170:171], v[170:171], v[180:181], v[180:181] op_sel_hi:[1,0,0]
	v_pk_fma_f32 v[172:173], v[172:173], v[180:181], v[180:181] op_sel_hi:[1,0,0]
	v_pk_fma_f32 v[174:175], v[174:175], v[180:181], v[180:181] op_sel_hi:[1,0,0]
	v_pk_fma_f32 v[176:177], v[176:177], v[180:181], v[180:181] op_sel_hi:[1,0,0]
	v_rcp_f32_e32 v170, v170
	v_rcp_f32_e32 v171, v171
	v_rcp_f32_e32 v172, v172
	v_rcp_f32_e32 v173, v173
	v_rcp_f32_e32 v174, v174
	v_rcp_f32_e32 v175, v175
	v_rcp_f32_e32 v176, v176
	v_rcp_f32_e32 v177, v177
	v_pk_mul_f32 v[86:87], v[94:95], v[86:87]
	v_pk_mul_f32 v[88:89], v[96:97], v[88:89]
	v_pk_mul_f32 v[82:83], v[90:91], v[82:83]
	v_pk_mul_f32 v[84:85], v[92:93], v[84:85]
; __device__ __forceinline__ u32x4 pack8(const f32x4& a, const f32x4& b) { u32x4 w; w.x = cvt_pk_bf16(a[0], a[1]); w.y = cvt_pk_bf16(a[2], a[3]); w.z = cvt_pk_bf16(b[0], b[1]); w.w = cvt_pk_bf16(b[2], b[3]); return w; }
; __device__ __forceinline__ float silu_mul(float g, float u) { return g * u * __builtin_amdgcn_rcpf(1.f + __builtin_amdgcn_exp2f(-1.4426950408889634f * g)); }
;     __device__ __forceinline__ void operator()(const f32x4 (&acc)[2][2][4][2], const Unit& u, int wr, int wc, int fr, int fq) const {
;         const int row0 = u.pm * BM + wr * 64 + fr, col0 = u.pn * HALF + wc * 32 + 8 * fq;
; #pragma unroll
;         for (int ai = 0; ai < 2; ++ai)
; #pragma unroll
;             for (int m = 0; m < 4; ++m) { f32x4 r0, r1; const float r = rs[row0 + ai * HALF + m * 16];
; #pragma unroll
;                 for (int e = 0; e < 4; ++e) { r0[e] = silu_mul(acc[ai][0][m][0][e] * r, acc[ai][1][m][0][e] * r); r1[e] = silu_mul(acc[ai][0][m][1][e] * r, acc[ai][1][m][1][e] * r); }
;                 *(u32x4*)(O + (size_t)(row0 + ai * HALF + m * 16) * ldc + col0) = pack8(r0, r1); }
	v_pk_mul_f32 v[86:87], v[86:87], v[170:171]
	v_pk_mul_f32 v[88:89], v[88:89], v[172:173]
	v_pk_mul_f32 v[82:83], v[82:83], v[174:175]
	v_pk_mul_f32 v[84:85], v[84:85], v[176:177]
	v_cvt_pk_bf16_f32 v182, v86, v87
	v_cvt_pk_bf16_f32 v183, v88, v89
	v_cvt_pk_bf16_f32 v184, v82, v83
	v_cvt_pk_bf16_f32 v185, v84, v85
	global_store_dwordx4 v[186:187], v[182:185], off
	s_mul_i32 s58, s51, 0x10
	v_lshl_add_u64 v[188:189], v[186:187], 0, s[58:59]
	v_mul_f32_e32 v178, 0xbfb8aa3b, v156
	v_mul_f32_e32 v180, v156, v156
	v_rcp_f32_e32 v180, v180
	v_pk_mul_f32 v[170:171], v[78:79], v[178:179] op_sel_hi:[1,0]
	v_pk_mul_f32 v[172:173], v[80:81], v[178:179] op_sel_hi:[1,0]
	v_pk_mul_f32 v[174:175], v[74:75], v[178:179] op_sel_hi:[1,0]
	v_pk_mul_f32 v[176:177], v[76:77], v[178:179] op_sel_hi:[1,0]
	v_exp_f32_e32 v170, v170
	v_exp_f32_e32 v171, v171
	v_exp_f32_e32 v172, v172
	v_exp_f32_e32 v173, v173
	v_exp_f32_e32 v174, v174
	v_exp_f32_e32 v175, v175
	v_exp_f32_e32 v176, v176
	v_exp_f32_e32 v177, v177
	v_pk_fma_f32 v[170:171], v[170:171], v[180:181], v[180:181] op_sel_hi:[1,0,0]
	v_pk_fma_f32 v[172:173], v[172:173], v[180:181], v[180:181] op_sel_hi:[1,0,0]
	v_pk_fma_f32 v[174:175], v[174:175], v[180:181], v[180:181] op_sel_hi:[1,0,0]
	v_pk_fma_f32 v[176:177], v[176:177], v[180:181], v[180:181] op_sel_hi:[1,0,0]
	v_rcp_f32_e32 v170, v170
	v_rcp_f32_e32 v171, v171
	v_rcp_f32_e32 v172, v172
	v_rcp_f32_e32 v173, v173
	v_rcp_f32_e32 v174, v174
	v_rcp_f32_e32 v175, v175
	v_rcp_f32_e32 v176, v176
	v_rcp_f32_e32 v177, v177
	v_pk_mul_f32 v[70:71], v[78:79], v[70:71]
	v_pk_mul_f32 v[72:73], v[80:81], v[72:73]
	v_pk_mul_f32 v[66:67], v[74:75], v[66:67]
	v_pk_mul_f32 v[68:69], v[76:77], v[68:69]
	v_pk_mul_f32 v[70:71], v[70:71], v[170:171]
	v_pk_mul_f32 v[72:73], v[72:73], v[172:173]
	v_pk_mul_f32 v[66:67], v[66:67], v[174:175]
	v_pk_mul_f32 v[68:69], v[68:69], v[176:177]
	v_cvt_pk_bf16_f32 v182, v70, v71
	v_cvt_pk_bf16_f32 v183, v72, v73
	v_cvt_pk_bf16_f32 v184, v66, v67
	v_cvt_pk_bf16_f32 v185, v68, v69
	global_store_dwordx4 v[188:189], v[182:185], off
	s_mul_i32 s58, s51, 0x50
	v_lshl_add_u64 v[186:187], v[188:189], 0, s[58:59]
	v_mul_f32_e32 v178, 0xbfb8aa3b, v157
	v_mul_f32_e32 v180, v157, v157
	v_rcp_f32_e32 v180, v180
	v_pk_mul_f32 v[170:171], v[62:63], v[178:179] op_sel_hi:[1,0]
	v_pk_mul_f32 v[172:173], v[64:65], v[178:179] op_sel_hi:[1,0]
	v_pk_mul_f32 v[174:175], v[58:59], v[178:179] op_sel_hi:[1,0]
	v_pk_mul_f32 v[176:177], v[60:61], v[178:179] op_sel_hi:[1,0]
	v_exp_f32_e32 v170, v170
	v_exp_f32_e32 v171, v171
	v_exp_f32_e32 v172, v172
	v_exp_f32_e32 v173, v173
	v_exp_f32_e32 v174, v174
	v_exp_f32_e32 v175, v175
	v_exp_f32_e32 v176, v176
	v_exp_f32_e32 v177, v177
	v_pk_fma_f32 v[170:171], v[170:171], v[180:181], v[180:181] op_sel_hi:[1,0,0]
	v_pk_fma_f32 v[172:173], v[172:173], v[180:181], v[180:181] op_sel_hi:[1,0,0]
	v_pk_fma_f32 v[174:175], v[174:175], v[180:181], v[180:181] op_sel_hi:[1,0,0]
	v_pk_fma_f32 v[176:177], v[176:177], v[180:181], v[180:181] op_sel_hi:[1,0,0]
	v_rcp_f32_e32 v170, v170
	v_rcp_f32_e32 v171, v171
	v_rcp_f32_e32 v172, v172
	v_rcp_f32_e32 v173, v173
	v_rcp_f32_e32 v174, v174
	v_rcp_f32_e32 v175, v175
	v_rcp_f32_e32 v176, v176
	v_rcp_f32_e32 v177, v177
	v_pk_mul_f32 v[54:55], v[62:63], v[54:55]
	v_pk_mul_f32 v[56:57], v[64:65], v[56:57]
	v_pk_mul_f32 v[50:51], v[58:59], v[50:51]
	v_pk_mul_f32 v[52:53], v[60:61], v[52:53]
	v_pk_mul_f32 v[54:55], v[54:55], v[170:171]
	v_pk_mul_f32 v[56:57], v[56:57], v[172:173]
	v_pk_mul_f32 v[50:51], v[50:51], v[174:175]
	v_pk_mul_f32 v[52:53], v[52:53], v[176:177]
	v_cvt_pk_bf16_f32 v182, v54, v55
	v_cvt_pk_bf16_f32 v183, v56, v57
	v_cvt_pk_bf16_f32 v184, v50, v51
	v_cvt_pk_bf16_f32 v185, v52, v53
	global_store_dwordx4 v[186:187], v[182:185], off
	s_mul_i32 s58, s51, 0x10
	v_lshl_add_u64 v[188:189], v[186:187], 0, s[58:59]
	v_mul_f32_e32 v178, 0xbfb8aa3b, v158
	v_mul_f32_e32 v180, v158, v158
	v_rcp_f32_e32 v180, v180
	v_pk_mul_f32 v[170:171], v[46:47], v[178:179] op_sel_hi:[1,0]
	v_pk_mul_f32 v[172:173], v[48:49], v[178:179] op_sel_hi:[1,0]
	v_pk_mul_f32 v[174:175], v[42:43], v[178:179] op_sel_hi:[1,0]
	v_pk_mul_f32 v[176:177], v[44:45], v[178:179] op_sel_hi:[1,0]
	v_exp_f32_e32 v170, v170
	v_exp_f32_e32 v171, v171
	v_exp_f32_e32 v172, v172
	v_exp_f32_e32 v173, v173
	v_exp_f32_e32 v174, v174
	v_exp_f32_e32 v175, v175
	v_exp_f32_e32 v176, v176
	v_exp_f32_e32 v177, v177
	v_pk_fma_f32 v[170:171], v[170:171], v[180:181], v[180:181] op_sel_hi:[1,0,0]
; __device__ __forceinline__ u32x4 pack8(const f32x4& a, const f32x4& b) { u32x4 w; w.x = cvt_pk_bf16(a[0], a[1]); w.y = cvt_pk_bf16(a[2], a[3]); w.z = cvt_pk_bf16(b[0], b[1]); w.w = cvt_pk_bf16(b[2], b[3]); return w; }
; __device__ __forceinline__ float silu_mul(float g, float u) { return g * u * __builtin_amdgcn_rcpf(1.f + __builtin_amdgcn_exp2f(-1.4426950408889634f * g)); }
; #define PG8_BAR __builtin_amdgcn_s_barrier()
;     __device__ __forceinline__ void operator()(const f32x4 (&acc)[2][2][4][2], const Unit& u, int wr, int wc, int fr, int fq) const {
;         const int row0 = u.pm * BM + wr * 64 + fr, col0 = u.pn * HALF + wc * 32 + 8 * fq;
; #pragma unroll
;         for (int ai = 0; ai < 2; ++ai)
; #pragma unroll
;             for (int m = 0; m < 4; ++m) { f32x4 r0, r1; const float r = rs[row0 + ai * HALF + m * 16];
; #pragma unroll
;                 for (int e = 0; e < 4; ++e) { r0[e] = silu_mul(acc[ai][0][m][0][e] * r, acc[ai][1][m][0][e] * r); r1[e] = silu_mul(acc[ai][0][m][1][e] * r, acc[ai][1][m][1][e] * r); }
;                 *(u32x4*)(O + (size_t)(row0 + ai * HALF + m * 16) * ldc + col0) = pack8(r0, r1); }
; template <class Epi, class Sched, bool ALIGN_EPI = false, bool SP2 = false>
; __device__ __forceinline__ void gemm_phase(PG8_LAS unsigned char* lds, const Gemm g, const Sched& S, const Epi& E, const int wv) {
;     ...
;         if constexpr (ALIGN_EPI) { if (wr == 0) PG8_BAR; }
;         if constexpr (!Epi::AFTER_DRAIN) { E(acc, cur, wr, wc, fr, fq); S.done(cur); }
;         if (!has_next) break;
; #pragma unroll
;         for (int a = 0; a < 2; ++a)
; #pragma unroll
;             for (int b = 0; b < 2; ++b)
; #pragma unroll
;                 for (int m = 0; m < 4; ++m)
; #pragma unroll
;                     for (int n = 0; n < 2; ++n) acc[a][b][m][n] = (f32x4){0.f, 0.f, 0.f, 0.f};
;         cur = nxt; cA = nA; cB = nB; ++ui;
;         if constexpr (ALIGN_EPI) { if (wr == 1) PG8_BAR; }
	v_pk_fma_f32 v[172:173], v[172:173], v[180:181], v[180:181] op_sel_hi:[1,0,0]
	v_pk_fma_f32 v[174:175], v[174:175], v[180:181], v[180:181] op_sel_hi:[1,0,0]
	v_pk_fma_f32 v[176:177], v[176:177], v[180:181], v[180:181] op_sel_hi:[1,0,0]
	v_rcp_f32_e32 v170, v170
	v_rcp_f32_e32 v171, v171
	v_rcp_f32_e32 v172, v172
	v_rcp_f32_e32 v173, v173
	v_rcp_f32_e32 v174, v174
	v_rcp_f32_e32 v175, v175
	v_rcp_f32_e32 v176, v176
	v_rcp_f32_e32 v177, v177
	v_pk_mul_f32 v[38:39], v[46:47], v[38:39]
	v_pk_mul_f32 v[40:41], v[48:49], v[40:41]
	v_pk_mul_f32 v[34:35], v[42:43], v[34:35]
	v_pk_mul_f32 v[36:37], v[44:45], v[36:37]
	v_pk_mul_f32 v[38:39], v[38:39], v[170:171]
	v_pk_mul_f32 v[40:41], v[40:41], v[172:173]
	v_pk_mul_f32 v[34:35], v[34:35], v[174:175]
	v_pk_mul_f32 v[36:37], v[36:37], v[176:177]
	v_cvt_pk_bf16_f32 v182, v38, v39
	v_cvt_pk_bf16_f32 v183, v40, v41
	v_cvt_pk_bf16_f32 v184, v34, v35
	v_cvt_pk_bf16_f32 v185, v36, v37
	global_store_dwordx4 v[188:189], v[182:185], off
	s_mul_i32 s58, s51, 0x10
	v_lshl_add_u64 v[186:187], v[188:189], 0, s[58:59]
	v_mul_f32_e32 v178, 0xbfb8aa3b, v159
	v_mul_f32_e32 v180, v159, v159
	v_rcp_f32_e32 v180, v180
	v_pk_mul_f32 v[170:171], v[30:31], v[178:179] op_sel_hi:[1,0]
	v_pk_mul_f32 v[172:173], v[32:33], v[178:179] op_sel_hi:[1,0]
	v_pk_mul_f32 v[174:175], v[26:27], v[178:179] op_sel_hi:[1,0]
	v_pk_mul_f32 v[176:177], v[28:29], v[178:179] op_sel_hi:[1,0]
	v_exp_f32_e32 v170, v170
	v_exp_f32_e32 v171, v171
	v_exp_f32_e32 v172, v172
	v_exp_f32_e32 v173, v173
	v_exp_f32_e32 v174, v174
	v_exp_f32_e32 v175, v175
	v_exp_f32_e32 v176, v176
	v_exp_f32_e32 v177, v177
	v_pk_fma_f32 v[170:171], v[170:171], v[180:181], v[180:181] op_sel_hi:[1,0,0]
	v_pk_fma_f32 v[172:173], v[172:173], v[180:181], v[180:181] op_sel_hi:[1,0,0]
	v_pk_fma_f32 v[174:175], v[174:175], v[180:181], v[180:181] op_sel_hi:[1,0,0]
	v_pk_fma_f32 v[176:177], v[176:177], v[180:181], v[180:181] op_sel_hi:[1,0,0]
	v_rcp_f32_e32 v170, v170
	v_rcp_f32_e32 v171, v171
	v_rcp_f32_e32 v172, v172
	v_rcp_f32_e32 v173, v173
	v_rcp_f32_e32 v174, v174
	v_rcp_f32_e32 v175, v175
	v_rcp_f32_e32 v176, v176
	v_rcp_f32_e32 v177, v177
	v_pk_mul_f32 v[22:23], v[30:31], v[22:23]
	v_pk_mul_f32 v[24:25], v[32:33], v[24:25]
	v_pk_mul_f32 v[18:19], v[26:27], v[18:19]
	v_pk_mul_f32 v[20:21], v[28:29], v[20:21]
	v_pk_mul_f32 v[22:23], v[22:23], v[170:171]
	v_pk_mul_f32 v[24:25], v[24:25], v[172:173]
	v_pk_mul_f32 v[18:19], v[18:19], v[174:175]
	v_pk_mul_f32 v[20:21], v[20:21], v[176:177]
	v_cvt_pk_bf16_f32 v182, v22, v23
	v_cvt_pk_bf16_f32 v183, v24, v25
	v_cvt_pk_bf16_f32 v184, v18, v19
	v_cvt_pk_bf16_f32 v185, v20, v21
	global_store_dwordx4 v[186:187], v[182:185], off
	s_mul_i32 s58, s51, 0x10
	v_lshl_add_u64 v[188:189], v[186:187], 0, s[58:59]
	v_mul_f32_e32 v178, 0xbfb8aa3b, v160
	v_mul_f32_e32 v180, v160, v160
	v_rcp_f32_e32 v180, v180
	v_pk_mul_f32 v[170:171], v[14:15], v[178:179] op_sel_hi:[1,0]
	v_pk_mul_f32 v[172:173], v[16:17], v[178:179] op_sel_hi:[1,0]
	v_pk_mul_f32 v[174:175], v[10:11], v[178:179] op_sel_hi:[1,0]
	v_pk_mul_f32 v[176:177], v[12:13], v[178:179] op_sel_hi:[1,0]
	v_exp_f32_e32 v170, v170
	v_exp_f32_e32 v171, v171
	v_exp_f32_e32 v172, v172
	v_exp_f32_e32 v173, v173
	v_exp_f32_e32 v174, v174
	v_exp_f32_e32 v175, v175
	v_exp_f32_e32 v176, v176
	v_exp_f32_e32 v177, v177
	v_pk_fma_f32 v[170:171], v[170:171], v[180:181], v[180:181] op_sel_hi:[1,0,0]
	v_pk_fma_f32 v[172:173], v[172:173], v[180:181], v[180:181] op_sel_hi:[1,0,0]
	v_pk_fma_f32 v[174:175], v[174:175], v[180:181], v[180:181] op_sel_hi:[1,0,0]
	v_pk_fma_f32 v[176:177], v[176:177], v[180:181], v[180:181] op_sel_hi:[1,0,0]
	v_rcp_f32_e32 v170, v170
	v_rcp_f32_e32 v171, v171
	v_rcp_f32_e32 v172, v172
	v_rcp_f32_e32 v173, v173
	v_rcp_f32_e32 v174, v174
	v_rcp_f32_e32 v175, v175
	v_rcp_f32_e32 v176, v176
	v_rcp_f32_e32 v177, v177
	v_pk_mul_f32 v[6:7], v[14:15], v[6:7]
	v_pk_mul_f32 v[8:9], v[16:17], v[8:9]
	v_pk_mul_f32 v[2:3], v[10:11], v[2:3]
	v_pk_mul_f32 v[4:5], v[12:13], v[4:5]
	v_pk_mul_f32 v[6:7], v[6:7], v[170:171]
	v_pk_mul_f32 v[8:9], v[8:9], v[172:173]
	v_pk_mul_f32 v[2:3], v[2:3], v[174:175]
	v_pk_mul_f32 v[4:5], v[4:5], v[176:177]
	v_cvt_pk_bf16_f32 v182, v6, v7
	v_cvt_pk_bf16_f32 v183, v8, v9
	v_cvt_pk_bf16_f32 v184, v2, v3
	v_cvt_pk_bf16_f32 v185, v4, v5
	global_store_dwordx4 v[188:189], v[182:185], off
	s_cbranch_vccnz .LBB0_222
	s_andn2_b64 vcc, exec, s[6:7]
	s_cbranch_vccnz .LBB0_221
	s_barrier
	s_branch .LBB0_221

; __device__ __forceinline__ float hswap_max(float v) { auto rr = __builtin_amdgcn_permlane32_swap(__float_as_uint(v), __float_as_uint(v), false, false); return fmaxf(__uint_as_float(rr[0]), __uint_as_float(rr[1])); }
; #define ATT_LOADK(t) do { st0 = *(const u32x4*)(ksrc + (size_t)(t) * 64 * T.ldk); if (rrole) st2 = *(const u32x4*)(rsrc + (size_t)(t) * 64 * 32); } while (0)
; #define ATT_STOREK(slot) do { LAS unsigned char* kb_ = lds + (slot) * ATT_KBYTES; *(LAS u32x4*)(kb_ + srow * KROWB + 16 * sc) = st0; if (rrole) *(LAS u32x4*)(kb_ + rr * KROWB + 128 + 16 * rc) = st2; } while (0)
; #define ATT_KREAD(slot) do { const LAS unsigned char* kb_ = lds + (slot) * ATT_KBYTES; \
;         _Pragma("unroll") for (int ks = 0; ks < KS; ++ks) { kf[2 * ks] = *(const LAS bf16x8*)(kb_ + koff + ks * 32); kf[2 * ks + 1] = *(const LAS bf16x8*)(kb_ + koff + 32 * KROWB + ks * 32); } } while (0)
; template <int MODE>
; __device__ __forceinline__ void attn_unit(LAS unsigned char* lds, const AttnT& T, int b, int q0, int qcol, int kcol, int vcol, int ocol, float sink_l2, const LAS float* btab, const int wv) {
;     ...
;     const bf16* vsrc = T.V + (rowbase + kvs + srow) * T.ldv + vcol + 8 * sc;
;     const bf16* ksrc = T.K + (rowbase + kvs + srow) * T.ldk + kcol + 8 * sc;
;     const bf16* rsrc = MODE == 0 ? T.KR + (rowbase + kvs + rr) * 32 + 8 * rc : nullptr;
;     ...
;     for (int r = 0; r < 16; ++r) { pA0[r] -= mrun; pA1[r] -= mrun; }
; #pragma unroll
;     for (int r = 0; r < 16; r += 2) ATT_SM4(pA0, pA1, r, kvs);
;     if (MODE == 0) {
;         float rm = fmaxf(fmaxf(pA0[0], pA1[0]), fmaxf(pA0[1], pA1[1]));
; #pragma unroll
;         for (int r = 2; r < 16; r += 2) rm = fmaxf(fmaxf(rm, fmaxf(pA0[r], pA1[r])), fmaxf(pA0[r + 1], pA1[r + 1]));
;         rm = hswap_max(rm); mrun = rm;
; #pragma unroll
;         for (int r = 0; r < 16; ++r) { pA0[r] -= rm; pA1[r] -= rm; }
;     }
; #pragma unroll
;     for (int r = 0; r < 16; ++r) negm[r] = -mrun;
;     ATT_KREAD(1);
;     __syncthreads();
;     ATT_LOADK(2); ATT_STOREK(0);
;     __syncthreads();
.LBB0_537:
	s_or_b64 exec, exec, s[26:27]
	s_waitcnt vmcnt(0)
	ds_write_b128 v221, v[34:37]
	s_and_saveexec_b64 s[0:1], s[6:7]
	s_xor_b64 s[6:7], exec, s[0:1]
	v_lshlrev_b32_e32 v220, 4, v39
	s_andn2_saveexec_b64 s[6:7], s[6:7]
	v_add3_u32 v34, 0, v49, v220
	ds_write_b128 v34, v[154:157] offset:128
	s_or_b64 exec, exec, s[6:7]
	v_max_f32_e32 v35, v50, v50
	v_max_f32_e32 v0, v0, v0
	v_max_f32_e32 v235, v0, v35
	v_lshlrev_b32_e32 v34, 3, v48
	v_sub_f32_e32 v50, v2, v235
	v_lshrrev_b32_e32 v2, 2, v46
	v_sub_f32_e32 v52, v4, v235
	v_sub_f32_e32 v51, v3, v235
	v_and_or_b32 v2, v2, 3, v34
	v_and_b32_e32 v3, 16, v46
	v_lshlrev_b32_e32 v4, 2, v46
	s_movk_i32 s0, 0xc0
	v_mul_u32_u24_e32 v2, 0xc0, v2
	v_and_or_b32 v3, v4, 12, v3
	s_lshl_b64 s[6:7], s[24:25], 1
	v_sub_f32_e32 v64, v16, v235
	v_mul_lo_u32 v0, v40, s0
	v_lshl_or_b32 v16, v3, 1, v2
	v_lshlrev_b64 v[2:3], 10, v[40:41]
	s_add_u32 s0, s8, s6
	v_lshl_or_b32 v2, v47, 4, v2
	s_addc_u32 s1, s9, s7
	v_lshl_add_u64 v[224:225], s[0:1], 0, v[2:3]
	v_lshlrev_b64 v[2:3], 6, v[42:43]
	v_sub_f32_e32 v63, v15, v235
	v_sub_f32_e32 v62, v14, v235
	v_lshl_or_b32 v2, v39, 4, v2
	v_mov_b32_e32 v14, v1
	v_mov_b32_e32 v15, v1
	v_sub_f32_e32 v97, v33, v235
	v_sub_f32_e32 v96, v32, v235
	v_sub_f32_e32 v95, v31, v235
	v_sub_f32_e32 v94, v30, v235
	v_sub_f32_e32 v93, v29, v235
	v_sub_f32_e32 v92, v28, v235
	v_sub_f32_e32 v91, v27, v235
	v_sub_f32_e32 v90, v26, v235
	v_sub_f32_e32 v89, v25, v235
	v_sub_f32_e32 v88, v24, v235
	v_sub_f32_e32 v87, v23, v235
	v_sub_f32_e32 v86, v22, v235
	v_sub_f32_e32 v85, v21, v235
	v_sub_f32_e32 v84, v20, v235
	v_sub_f32_e32 v83, v19, v235
	v_sub_f32_e32 v82, v18, v235
	v_sub_f32_e32 v65, v17, v235
	v_sub_f32_e32 v61, v13, v235
	v_sub_f32_e32 v60, v12, v235
	v_sub_f32_e32 v59, v11, v235
	v_sub_f32_e32 v58, v10, v235
	v_sub_f32_e32 v57, v9, v235
	v_sub_f32_e32 v56, v8, v235
	v_sub_f32_e32 v55, v7, v235
	v_sub_f32_e32 v54, v6, v235
	v_sub_f32_e32 v53, v5, v235
	v_add_u32_e32 v17, 0, v0
	v_lshl_add_u64 v[226:227], s[8:9], 0, v[2:3]
	v_mov_b32_e32 v0, v1
	v_mov_b32_e32 v2, v1
	v_mov_b32_e32 v3, v1
	v_mov_b32_e32 v4, v1
	v_mov_b32_e32 v5, v1
	v_mov_b32_e32 v6, v1
	v_mov_b32_e32 v7, v1
	v_mov_b32_e32 v8, v1
	v_mov_b32_e32 v9, v1
	v_mov_b32_e32 v10, v1
	v_mov_b32_e32 v11, v1
	v_mov_b32_e32 v12, v1
	v_mov_b32_e32 v13, v1
	v_mov_b64_e32 v[32:33], v[14:15]
	v_xor_b32_e32 v66, 0x80000000, v235
	v_add_u32_e32 v231, 0, v16
	v_add_u32_e32 v234, v17, v38
	v_mov_b64_e32 v[30:31], v[12:13]
	v_mov_b64_e32 v[28:29], v[10:11]
	v_mov_b64_e32 v[26:27], v[8:9]
	v_mov_b64_e32 v[24:25], v[6:7]
	v_mov_b64_e32 v[22:23], v[4:5]
	v_mov_b64_e32 v[20:21], v[2:3]
	v_mov_b64_e32 v[18:19], v[0:1]
	v_mov_b64_e32 v[16:17], v[14:15]
	v_add_u32_e32 v241, 0, v49
	s_mov_b32 s35, 0
	v_mov_b32_e32 v242, 0
	v_mov_b64_e32 v[14:15], v[12:13]
	v_mov_b64_e32 v[12:13], v[10:11]
	v_mov_b64_e32 v[10:11], v[8:9]
	v_mov_b64_e32 v[8:9], v[6:7]
	v_mov_b64_e32 v[6:7], v[4:5]
	v_mov_b64_e32 v[4:5], v[2:3]
	v_mov_b64_e32 v[2:3], v[0:1]
	v_mov_b32_e32 v67, v66
	v_mov_b32_e32 v68, v66
	v_mov_b32_e32 v69, v66
	v_mov_b32_e32 v70, v66
	v_mov_b32_e32 v71, v66
	v_mov_b32_e32 v72, v66
	v_mov_b32_e32 v73, v66
	v_mov_b32_e32 v74, v66
	v_mov_b32_e32 v75, v66
	v_mov_b32_e32 v76, v66
	v_mov_b32_e32 v77, v66
	v_mov_b32_e32 v78, v66
	v_mov_b32_e32 v79, v66
	v_mov_b32_e32 v80, v66
	v_mov_b32_e32 v81, v66
	s_waitcnt lgkmcnt(0)
	s_barrier
	v_lshl_add_u64 v[228:229], v[224:225], 0, s[70:71]
	s_mov_b64 s[0:1], 0x17730000
	v_lshl_add_u64 v[250:251], v[228:229], 0, s[0:1]
	s_mov_b64 s[0:1], 0x17f10000
	v_lshl_add_u64 v[252:253], v[228:229], 0, s[0:1]
	s_branch .LBB0_544

.LBB0_543:
	s_add_i32 s35, s35, 2
	s_mov_b64 s[0:1], 0x2000
	s_cmpk_lt_u32 s35, 0x7e
	v_lshl_add_u64 v[226:227], v[226:227], 0, s[0:1]
	s_waitcnt vmcnt(0)
	ds_write_b128 v230, v[206:209] offset:26624
	s_waitcnt lgkmcnt(0)
	s_barrier
	s_cbranch_scc0 .LBB0_559
.LBB0_544:
	global_load_dwordx4 v[162:165], v[250:251], off
	s_and_saveexec_b64 s[24:25], s[4:5]
	s_cbranch_execz .LBB0_546
	v_lshl_add_u64 v[34:35], v[226:227], 0, s[70:71]
	v_add_co_u32_e32 v34, vcc, 0x15e03000, v34
	s_nop 1
	v_addc_co_u32_e32 v35, vcc, 0, v35, vcc
	global_load_dwordx4 v[154:157], v[34:35], off
.LBB0_546:
	s_or_b64 exec, exec, s[24:25]
	global_load_dwordx4 v[206:209], v[252:253], off
	s_mov_b64 s[0:1], 0x10000
	v_lshl_add_u64 v[250:251], v[250:251], 0, s[0:1]
	v_lshl_add_u64 v[252:253], v[252:253], 0, s[0:1]
	v_exp_f32_e32 v0, v82
	v_exp_f32_e32 v34, v83
	v_mfma_f32_32x32x16_bf16 v[114:129], v[98:101], v[150:153], v[66:81]
	v_exp_f32_e32 v36, v85
	v_add_f32_e32 v35, v34, v0
	v_cvt_pk_bf16_f32 v34, v0, v34
	v_exp_f32_e32 v0, v84
	s_nop 0
	v_add_f32_e32 v35, v0, v35
	v_add_f32_e32 v37, v36, v35
	v_cvt_pk_bf16_f32 v35, v0, v36
	v_exp_f32_e32 v0, v86
	v_mfma_f32_32x32x16_bf16 v[98:113], v[202:205], v[150:153], v[66:81]
	v_exp_f32_e32 v36, v87
	v_exp_f32_e32 v38, v88
	v_exp_f32_e32 v39, v89
	v_add_f32_e32 v37, v0, v37
	v_add_f32_e32 v37, v36, v37
	v_cvt_pk_bf16_f32 v36, v0, v36
	v_add_f32_e32 v0, v38, v37
	v_add_f32_e32 v0, v39, v0
	v_cvt_pk_bf16_f32 v37, v38, v39
	v_exp_f32_e32 v38, v90
	v_exp_f32_e32 v39, v91
	v_mfma_f32_32x32x16_bf16 v[114:129], v[198:201], v[146:149], v[114:129]
	v_exp_f32_e32 v40, v93
	v_add_f32_e32 v0, v38, v0
	v_add_f32_e32 v0, v39, v0
	v_cvt_pk_bf16_f32 v38, v38, v39
	v_exp_f32_e32 v39, v92
	s_nop 0
	v_add_f32_e32 v0, v39, v0
	v_add_f32_e32 v0, v40, v0
	v_cvt_pk_bf16_f32 v39, v39, v40
	v_exp_f32_e32 v40, v94
	v_exp_f32_e32 v41, v95
	v_mfma_f32_32x32x16_bf16 v[98:113], v[194:197], v[146:149], v[98:113]
	v_exp_f32_e32 v42, v97
	v_add_f32_e32 v0, v40, v0
	v_add_f32_e32 v0, v41, v0
	v_cvt_pk_bf16_f32 v40, v40, v41
	v_exp_f32_e32 v41, v96
	s_nop 0
	v_add_f32_e32 v0, v41, v0
	v_add_f32_e32 v0, v42, v0
	v_cvt_pk_bf16_f32 v41, v41, v42
	v_mfma_f32_32x32x16_bf16 v[114:129], v[190:193], v[142:145], v[114:129]
	ds_read_b64_tr_b16 v[82:83], v231 offset:26624
	ds_read_b64_tr_b16 v[84:85], v231 offset:27392
	ds_read_b64_tr_b16 v[46:47], v231 offset:26688
	ds_read_b64_tr_b16 v[48:49], v231 offset:27456
	v_exp_f32_e32 v42, v50
	v_exp_f32_e32 v43, v51
	v_add_f32_e32 v0, v42, v0
	v_add_f32_e32 v0, v43, v0
	v_cvt_pk_bf16_f32 v42, v42, v43
	v_mfma_f32_32x32x16_bf16 v[98:113], v[186:189], v[142:145], v[98:113]
	v_exp_f32_e32 v43, v52
	v_exp_f32_e32 v44, v53
	ds_read_b64_tr_b16 v[86:87], v231 offset:29696
	ds_read_b64_tr_b16 v[88:89], v231 offset:30464
	v_add_f32_e32 v0, v43, v0
	v_add_f32_e32 v0, v44, v0
	v_cvt_pk_bf16_f32 v43, v43, v44
	v_mfma_f32_32x32x16_bf16 v[114:129], v[182:185], v[138:141], v[114:129]
	v_exp_f32_e32 v44, v54
	v_exp_f32_e32 v45, v55
	ds_read_b64_tr_b16 v[90:91], v231 offset:29760
	ds_read_b64_tr_b16 v[92:93], v231 offset:30528
	v_add_f32_e32 v0, v44, v0
	v_add_f32_e32 v0, v45, v0
	v_cvt_pk_bf16_f32 v44, v44, v45
	v_mfma_f32_32x32x16_bf16 v[98:113], v[178:181], v[138:141], v[98:113]
	v_exp_f32_e32 v45, v56
	v_exp_f32_e32 v50, v57
	ds_read_b64_tr_b16 v[94:95], v231 offset:32768
	ds_read_b64_tr_b16 v[96:97], v231 offset:33536
	v_add_f32_e32 v0, v45, v0
	v_add_f32_e32 v0, v50, v0
	v_cvt_pk_bf16_f32 v45, v45, v50
	v_mfma_f32_32x32x16_bf16 v[114:129], v[174:177], v[134:137], v[114:129]
	v_exp_f32_e32 v50, v58
	v_exp_f32_e32 v51, v59
	ds_read_b64_tr_b16 v[210:211], v231 offset:32832
	ds_read_b64_tr_b16 v[212:213], v231 offset:33600
	v_add_f32_e32 v0, v50, v0
	v_add_f32_e32 v0, v51, v0
	v_cvt_pk_bf16_f32 v54, v50, v51
	v_mfma_f32_32x32x16_bf16 v[98:113], v[170:173], v[134:137], v[98:113]
	v_exp_f32_e32 v50, v60
	v_exp_f32_e32 v51, v61
	ds_read_b64_tr_b16 v[58:59], v231 offset:35840
	ds_read_b64_tr_b16 v[60:61], v231 offset:36608
	v_add_f32_e32 v0, v50, v0
	v_add_f32_e32 v0, v51, v0
	v_cvt_pk_bf16_f32 v55, v50, v51
	v_mfma_f32_32x32x16_bf16 v[114:129], v[166:169], v[130:133], v[114:129]
	v_exp_f32_e32 v50, v62
	v_exp_f32_e32 v51, v63
	ds_read_b64_tr_b16 v[214:215], v231 offset:35904
	ds_read_b64_tr_b16 v[216:217], v231 offset:36672
	v_add_f32_e32 v0, v50, v0
	v_add_f32_e32 v0, v51, v0
	v_cvt_pk_bf16_f32 v56, v50, v51
	v_mfma_f32_32x32x16_bf16 v[98:113], v[158:161], v[130:133], v[98:113]
	v_exp_f32_e32 v50, v64
	v_exp_f32_e32 v51, v65
	v_add_f32_e32 v0, v50, v0
	v_add_f32_e32 v62, v51, v0
	v_cvt_pk_bf16_f32 v57, v50, v51
	s_waitcnt lgkmcnt(14)
	v_mfma_f32_32x32x16_bf16 v[18:33], v[82:85], v[34:37], v[18:33]
	ds_read_b128 v[50:53], v233
	ds_read_b128 v[198:201], v233 offset:6656
	v_add_f32_e32 v0, v242, v62
	s_waitcnt lgkmcnt(14)
	v_mfma_f32_32x32x16_bf16 v[2:17], v[46:49], v[34:37], v[2:17]
	ds_read_b128 v[202:205], v233 offset:32
	ds_read_b128 v[194:197], v233 offset:6688
	s_waitcnt lgkmcnt(14)
	v_mfma_f32_32x32x16_bf16 v[18:33], v[86:89], v[38:41], v[18:33]
	ds_read_b128 v[190:193], v233 offset:64
	ds_read_b128 v[186:189], v233 offset:6720
	s_waitcnt lgkmcnt(14)
	v_mfma_f32_32x32x16_bf16 v[2:17], v[90:93], v[38:41], v[2:17]
	ds_read_b128 v[182:185], v233 offset:96
	ds_read_b128 v[178:181], v233 offset:6752
	s_waitcnt lgkmcnt(14)
	v_mfma_f32_32x32x16_bf16 v[18:33], v[94:97], v[42:45], v[18:33]
	ds_read_b128 v[174:177], v233 offset:128
	ds_read_b128 v[170:173], v233 offset:6784
	s_waitcnt lgkmcnt(14)
	v_mfma_f32_32x32x16_bf16 v[2:17], v[210:213], v[42:45], v[2:17]
	ds_read_b128 v[166:169], v233 offset:160
	ds_read_b128 v[158:161], v233 offset:6816
	s_waitcnt lgkmcnt(14)
	v_mfma_f32_32x32x16_bf16 v[18:33], v[58:61], v[54:57], v[18:33]
	s_waitcnt lgkmcnt(12)
	v_mfma_f32_32x32x16_bf16 v[2:17], v[214:217], v[54:57], v[2:17]
	v_mov_b32_e32 v34, v62
	s_nop 1
	v_permlane32_swap_b32_e32 v62, v34
	v_max_f32_e32 v34, v62, v34
	v_cmp_lt_f32_e32 vcc, s74, v34
	s_cbranch_vccz .LBB0_558
	v_frexp_exp_i32_f32_e32 v34, v34
	v_cvt_f32_i32_e32 v34, v34
	v_cndmask_b32_e32 v35, 0, v34, vcc
	v_exp_f32_e64 v36, -v35
	v_add_f32_e32 v235, v235, v35
	v_xor_b32_e32 v34, 0x80000000, v235
	v_sub_f32_e32 v129, v129, v35
	v_pk_mul_f32 v[32:33], v[32:33], v[36:37] op_sel_hi:[1,0]
	v_pk_mul_f32 v[30:31], v[30:31], v[36:37] op_sel_hi:[1,0]
	v_pk_mul_f32 v[28:29], v[28:29], v[36:37] op_sel_hi:[1,0]
	v_pk_mul_f32 v[26:27], v[26:27], v[36:37] op_sel_hi:[1,0]
	v_pk_mul_f32 v[24:25], v[24:25], v[36:37] op_sel_hi:[1,0]
	v_pk_mul_f32 v[22:23], v[22:23], v[36:37] op_sel_hi:[1,0]
	v_pk_mul_f32 v[20:21], v[20:21], v[36:37] op_sel_hi:[1,0]
	v_pk_mul_f32 v[18:19], v[18:19], v[36:37] op_sel_hi:[1,0]
	v_pk_mul_f32 v[16:17], v[16:17], v[36:37] op_sel_hi:[1,0]
	v_pk_mul_f32 v[14:15], v[14:15], v[36:37] op_sel_hi:[1,0]
	v_pk_mul_f32 v[12:13], v[12:13], v[36:37] op_sel_hi:[1,0]
	v_pk_mul_f32 v[10:11], v[10:11], v[36:37] op_sel_hi:[1,0]
	v_pk_mul_f32 v[8:9], v[8:9], v[36:37] op_sel_hi:[1,0]
	v_pk_mul_f32 v[6:7], v[6:7], v[36:37] op_sel_hi:[1,0]
	v_pk_mul_f32 v[4:5], v[4:5], v[36:37] op_sel_hi:[1,0]
	v_pk_mul_f32 v[2:3], v[2:3], v[36:37] op_sel_hi:[1,0]
	v_sub_f32_e32 v128, v128, v35
	v_sub_f32_e32 v127, v127, v35
	v_sub_f32_e32 v126, v126, v35
	v_sub_f32_e32 v125, v125, v35
	v_sub_f32_e32 v124, v124, v35
	v_sub_f32_e32 v123, v123, v35
	v_sub_f32_e32 v122, v122, v35
	v_sub_f32_e32 v121, v121, v35
	v_sub_f32_e32 v120, v120, v35
	v_sub_f32_e32 v119, v119, v35
	v_sub_f32_e32 v118, v118, v35
	v_sub_f32_e32 v117, v117, v35
	v_sub_f32_e32 v116, v116, v35
	v_sub_f32_e32 v115, v115, v35
	v_sub_f32_e32 v114, v114, v35
	v_sub_f32_e32 v113, v113, v35
	v_sub_f32_e32 v112, v112, v35
	v_sub_f32_e32 v111, v111, v35
	v_sub_f32_e32 v110, v110, v35
	v_sub_f32_e32 v109, v109, v35
	v_sub_f32_e32 v108, v108, v35
	v_sub_f32_e32 v107, v107, v35
	v_sub_f32_e32 v106, v106, v35
	v_sub_f32_e32 v105, v105, v35
	v_sub_f32_e32 v104, v104, v35
	v_sub_f32_e32 v103, v103, v35
	v_sub_f32_e32 v102, v102, v35
	v_sub_f32_e32 v101, v101, v35
	v_sub_f32_e32 v100, v100, v35
	v_sub_f32_e32 v99, v99, v35
	v_sub_f32_e32 v98, v98, v35
	v_mul_f32_e32 v0, v0, v36
	v_mov_b32_e32 v35, v34
	v_mov_b32_e32 v36, v34
	v_mov_b32_e32 v37, v34
	v_mov_b32_e32 v38, v34
	v_mov_b32_e32 v39, v34
	v_mov_b32_e32 v40, v34
	v_mov_b32_e32 v41, v34
	v_mov_b32_e32 v42, v34
	v_mov_b32_e32 v43, v34
	v_mov_b32_e32 v44, v34
	v_mov_b32_e32 v45, v34
	v_mov_b32_e32 v46, v34
	v_mov_b32_e32 v47, v34
	v_mov_b32_e32 v48, v34
	v_mov_b32_e32 v49, v34
	v_mov_b32_e32 v66, v34
	v_mov_b32_e32 v67, v34
	v_mov_b32_e32 v68, v34
	v_mov_b32_e32 v69, v34
	v_mov_b32_e32 v70, v34
	v_mov_b32_e32 v71, v34
	v_mov_b32_e32 v72, v34
	v_mov_b32_e32 v73, v34
	v_mov_b32_e32 v74, v34
	v_mov_b32_e32 v75, v34
	v_mov_b32_e32 v76, v34
	v_mov_b32_e32 v77, v34
	v_mov_b32_e32 v78, v34
	v_mov_b32_e32 v79, v34
	v_mov_b32_e32 v80, v34
	v_mov_b32_e32 v81, v34
	s_waitcnt vmcnt(1)
	ds_write_b128 v232, v[162:165] offset:13312
	s_and_saveexec_b64 s[24:25], s[4:5]

.LBB0_549:
	s_or_b64 exec, exec, s[24:25]
	s_cmpk_lt_u32 s35, 0x7c
	s_cselect_b64 s[24:25], -1, 0
	s_cmpk_gt_u32 s35, 0x7b
	s_waitcnt vmcnt(0)
	ds_write_b128 v234, v[206:209] offset:38912
	s_waitcnt lgkmcnt(0)
	s_barrier
	s_cbranch_scc1 .LBB0_553
	global_load_dwordx4 v[162:165], v[250:251], off
	s_and_saveexec_b64 s[26:27], s[4:5]
	s_cbranch_execz .LBB0_552
	v_lshl_add_u64 v[54:55], v[226:227], 0, s[70:71]
	v_add_co_u32_e32 v54, vcc, 0x15e04000, v54
	s_nop 1
	v_addc_co_u32_e32 v55, vcc, 0, v55, vcc
	global_load_dwordx4 v[154:157], v[54:55], off

.LBB0_553:
	global_load_dwordx4 v[206:209], v[252:253], off
	s_mov_b64 s[0:1], 0x10000
	v_lshl_add_u64 v[250:251], v[250:251], 0, s[0:1]
	v_lshl_add_u64 v[252:253], v[252:253], 0, s[0:1]
	v_mfma_f32_32x32x16_bf16 v[82:97], v[50:53], v[150:153], v[66:81]
	v_exp_f32_e32 v50, v114
	v_exp_f32_e32 v51, v115
	v_add_f32_e32 v52, 0, v50
	v_cvt_pk_bf16_f32 v114, v50, v51
	v_exp_f32_e32 v50, v116
	v_add_f32_e32 v52, v51, v52
	v_exp_f32_e32 v51, v117
	v_add_f32_e32 v52, v50, v52
	v_add_f32_e32 v52, v51, v52
	v_cvt_pk_bf16_f32 v115, v50, v51
	v_exp_f32_e32 v116, v118
	v_exp_f32_e32 v117, v119
	v_exp_f32_e32 v118, v120
	v_exp_f32_e32 v119, v121
	v_add_f32_e32 v50, v116, v52
	v_add_f32_e32 v120, v117, v50
	v_mfma_f32_32x32x16_bf16 v[50:65], v[198:201], v[150:153], v[66:81]
	v_cvt_pk_bf16_f32 v116, v116, v117
	v_add_f32_e32 v117, v118, v120
	v_add_f32_e32 v120, v119, v117
	v_cvt_pk_bf16_f32 v117, v118, v119
	v_exp_f32_e32 v118, v122
	v_exp_f32_e32 v119, v123
	v_mfma_f32_32x32x16_bf16 v[82:97], v[202:205], v[146:149], v[82:97]
	v_exp_f32_e32 v121, v125
	v_add_f32_e32 v120, v118, v120
	v_add_f32_e32 v120, v119, v120
	v_cvt_pk_bf16_f32 v118, v118, v119
	v_exp_f32_e32 v119, v124
	s_nop 0
	v_add_f32_e32 v120, v119, v120
	v_add_f32_e32 v120, v121, v120
	v_cvt_pk_bf16_f32 v119, v119, v121
	v_exp_f32_e32 v121, v126
	v_exp_f32_e32 v122, v127
	v_mfma_f32_32x32x16_bf16 v[50:65], v[194:197], v[146:149], v[50:65]
	v_add_f32_e32 v120, v121, v120
	v_add_f32_e32 v123, v122, v120
	v_cvt_pk_bf16_f32 v120, v121, v122
	v_exp_f32_e32 v121, v128
	v_exp_f32_e32 v122, v129
	v_add_f32_e32 v123, v121, v123
	v_add_f32_e32 v123, v122, v123
	v_cvt_pk_bf16_f32 v121, v121, v122
	v_mfma_f32_32x32x16_bf16 v[82:97], v[190:193], v[142:145], v[82:97]
	ds_read_b64_tr_b16 v[190:191], v231 offset:38912
	ds_read_b64_tr_b16 v[192:193], v231 offset:39680
	ds_read_b64_tr_b16 v[126:127], v231 offset:38976
	ds_read_b64_tr_b16 v[128:129], v231 offset:39744
	v_exp_f32_e32 v98, v98
	v_exp_f32_e32 v99, v99
	v_add_f32_e32 v122, v98, v123
	v_add_f32_e32 v123, v99, v122
	v_cvt_pk_bf16_f32 v122, v98, v99
	v_mfma_f32_32x32x16_bf16 v[50:65], v[186:189], v[142:145], v[50:65]
	v_exp_f32_e32 v98, v100
	v_exp_f32_e32 v99, v101
	ds_read_b64_tr_b16 v[186:187], v231 offset:41984
	ds_read_b64_tr_b16 v[188:189], v231 offset:42752
	v_add_f32_e32 v100, v98, v123
	v_add_f32_e32 v100, v99, v100
	v_cvt_pk_bf16_f32 v123, v98, v99
	v_mfma_f32_32x32x16_bf16 v[82:97], v[182:185], v[138:141], v[82:97]
	v_exp_f32_e32 v98, v102
	v_exp_f32_e32 v99, v103
	ds_read_b64_tr_b16 v[182:183], v231 offset:42048
	ds_read_b64_tr_b16 v[184:185], v231 offset:42816
	v_add_f32_e32 v100, v98, v100
	v_add_f32_e32 v100, v99, v100
	v_cvt_pk_bf16_f32 v124, v98, v99
	v_mfma_f32_32x32x16_bf16 v[50:65], v[178:181], v[138:141], v[50:65]
	v_exp_f32_e32 v98, v104
	v_exp_f32_e32 v99, v105
	ds_read_b64_tr_b16 v[210:211], v231 offset:45056
	ds_read_b64_tr_b16 v[212:213], v231 offset:45824
	v_add_f32_e32 v100, v98, v100
	v_add_f32_e32 v100, v99, v100
	v_cvt_pk_bf16_f32 v125, v98, v99
	v_mfma_f32_32x32x16_bf16 v[82:97], v[174:177], v[134:137], v[82:97]
	v_exp_f32_e32 v98, v106
	v_exp_f32_e32 v99, v107
	ds_read_b64_tr_b16 v[214:215], v231 offset:45120
	ds_read_b64_tr_b16 v[216:217], v231 offset:45888
	v_add_f32_e32 v100, v98, v100
	v_add_f32_e32 v100, v99, v100
	v_cvt_pk_bf16_f32 v102, v98, v99
	v_mfma_f32_32x32x16_bf16 v[50:65], v[170:173], v[134:137], v[50:65]
	v_exp_f32_e32 v98, v108
	v_exp_f32_e32 v99, v109
	ds_read_b64_tr_b16 v[106:107], v231 offset:48128
	ds_read_b64_tr_b16 v[108:109], v231 offset:48896
	v_add_f32_e32 v100, v98, v100
	v_add_f32_e32 v100, v99, v100
	v_cvt_pk_bf16_f32 v103, v98, v99
	v_mfma_f32_32x32x16_bf16 v[82:97], v[166:169], v[130:133], v[82:97]
	v_exp_f32_e32 v98, v110
	v_exp_f32_e32 v99, v111
	ds_read_b64_tr_b16 v[244:245], v231 offset:48192
	ds_read_b64_tr_b16 v[246:247], v231 offset:48960
	v_add_f32_e32 v100, v98, v100
	v_add_f32_e32 v100, v99, v100
	v_cvt_pk_bf16_f32 v104, v98, v99
	v_mfma_f32_32x32x16_bf16 v[50:65], v[158:161], v[130:133], v[50:65]
	v_exp_f32_e32 v98, v112
	v_exp_f32_e32 v99, v113
	v_add_f32_e32 v100, v98, v100
	v_add_f32_e32 v110, v99, v100
	v_cvt_pk_bf16_f32 v105, v98, v99
	s_waitcnt lgkmcnt(14)
	v_mfma_f32_32x32x16_bf16 v[18:33], v[190:193], v[114:117], v[18:33]
	ds_read_b128 v[98:101], v233 offset:13312
	ds_read_b128 v[202:205], v233 offset:19968
	v_add_f32_e32 v242, v0, v110
	s_waitcnt lgkmcnt(14)
	v_mfma_f32_32x32x16_bf16 v[2:17], v[126:129], v[114:117], v[2:17]
	ds_read_b128 v[198:201], v233 offset:13344
	ds_read_b128 v[194:197], v233 offset:20000
	s_waitcnt lgkmcnt(14)
	v_mfma_f32_32x32x16_bf16 v[18:33], v[186:189], v[118:121], v[18:33]
	ds_read_b128 v[190:193], v233 offset:13376
	ds_read_b128 v[186:189], v233 offset:20032
	s_waitcnt lgkmcnt(14)
	v_mfma_f32_32x32x16_bf16 v[2:17], v[182:185], v[118:121], v[2:17]
	ds_read_b128 v[182:185], v233 offset:13408
	ds_read_b128 v[178:181], v233 offset:20064
	s_waitcnt lgkmcnt(14)
	v_mfma_f32_32x32x16_bf16 v[18:33], v[210:213], v[122:125], v[18:33]
	ds_read_b128 v[174:177], v233 offset:13440
	ds_read_b128 v[170:173], v233 offset:20096
	s_waitcnt lgkmcnt(14)
	v_mfma_f32_32x32x16_bf16 v[2:17], v[214:217], v[122:125], v[2:17]
	ds_read_b128 v[166:169], v233 offset:13472
	ds_read_b128 v[158:161], v233 offset:20128
	s_waitcnt lgkmcnt(14)
	v_mfma_f32_32x32x16_bf16 v[18:33], v[106:109], v[102:105], v[18:33]
	s_waitcnt lgkmcnt(12)
	v_mfma_f32_32x32x16_bf16 v[2:17], v[244:247], v[102:105], v[2:17]
	v_mov_b32_e32 v0, v110
	s_nop 1
	v_permlane32_swap_b32_e32 v110, v0
	v_max_f32_e32 v0, v110, v0
	v_cmp_lt_f32_e32 vcc, s74, v0
	s_cbranch_vccz .LBB0_555
	v_frexp_exp_i32_f32_e32 v0, v0
	v_cvt_f32_i32_e32 v0, v0
	v_cndmask_b32_e32 v35, 0, v0, vcc
	v_exp_f32_e64 v0, -v35
	v_add_f32_e32 v235, v235, v35
	v_xor_b32_e32 v34, 0x80000000, v235
	v_sub_f32_e32 v97, v97, v35
	v_pk_mul_f32 v[32:33], v[32:33], v[0:1] op_sel_hi:[1,0]
	v_pk_mul_f32 v[30:31], v[30:31], v[0:1] op_sel_hi:[1,0]
	v_pk_mul_f32 v[28:29], v[28:29], v[0:1] op_sel_hi:[1,0]
	v_pk_mul_f32 v[26:27], v[26:27], v[0:1] op_sel_hi:[1,0]
	v_pk_mul_f32 v[24:25], v[24:25], v[0:1] op_sel_hi:[1,0]
	v_pk_mul_f32 v[22:23], v[22:23], v[0:1] op_sel_hi:[1,0]
	v_pk_mul_f32 v[20:21], v[20:21], v[0:1] op_sel_hi:[1,0]
	v_pk_mul_f32 v[18:19], v[18:19], v[0:1] op_sel_hi:[1,0]
	v_pk_mul_f32 v[16:17], v[16:17], v[0:1] op_sel_hi:[1,0]
	v_pk_mul_f32 v[14:15], v[14:15], v[0:1] op_sel_hi:[1,0]
	v_pk_mul_f32 v[12:13], v[12:13], v[0:1] op_sel_hi:[1,0]
	v_pk_mul_f32 v[10:11], v[10:11], v[0:1] op_sel_hi:[1,0]
	v_pk_mul_f32 v[8:9], v[8:9], v[0:1] op_sel_hi:[1,0]
	v_pk_mul_f32 v[6:7], v[6:7], v[0:1] op_sel_hi:[1,0]
	v_pk_mul_f32 v[4:5], v[4:5], v[0:1] op_sel_hi:[1,0]
	v_pk_mul_f32 v[2:3], v[2:3], v[0:1] op_sel_hi:[1,0]
	v_sub_f32_e32 v96, v96, v35
	v_sub_f32_e32 v95, v95, v35
	v_sub_f32_e32 v94, v94, v35
	v_sub_f32_e32 v93, v93, v35
	v_sub_f32_e32 v92, v92, v35
	v_sub_f32_e32 v91, v91, v35
	v_sub_f32_e32 v90, v90, v35
	v_sub_f32_e32 v89, v89, v35
	v_sub_f32_e32 v88, v88, v35
	v_sub_f32_e32 v87, v87, v35
	v_sub_f32_e32 v86, v86, v35
	v_sub_f32_e32 v85, v85, v35
	v_sub_f32_e32 v84, v84, v35
	v_sub_f32_e32 v83, v83, v35
	v_sub_f32_e32 v82, v82, v35
	v_sub_f32_e32 v65, v65, v35
	v_sub_f32_e32 v64, v64, v35
	v_sub_f32_e32 v63, v63, v35
	v_sub_f32_e32 v62, v62, v35
	v_sub_f32_e32 v61, v61, v35
	v_sub_f32_e32 v60, v60, v35
	v_sub_f32_e32 v59, v59, v35
	v_sub_f32_e32 v58, v58, v35
	v_sub_f32_e32 v57, v57, v35
	v_sub_f32_e32 v56, v56, v35
	v_sub_f32_e32 v55, v55, v35
	v_sub_f32_e32 v54, v54, v35
	v_sub_f32_e32 v53, v53, v35
	v_sub_f32_e32 v52, v52, v35
	v_sub_f32_e32 v51, v51, v35
	v_sub_f32_e32 v50, v50, v35
	v_mul_f32_e32 v242, v242, v0
	v_mov_b32_e32 v35, v34
	v_mov_b32_e32 v36, v34
	v_mov_b32_e32 v37, v34
	v_mov_b32_e32 v38, v34
	v_mov_b32_e32 v39, v34
	v_mov_b32_e32 v40, v34
	v_mov_b32_e32 v41, v34
	v_mov_b32_e32 v42, v34
	v_mov_b32_e32 v43, v34
	v_mov_b32_e32 v44, v34
	v_mov_b32_e32 v45, v34
	v_mov_b32_e32 v46, v34
	v_mov_b32_e32 v47, v34
	v_mov_b32_e32 v48, v34
	v_mov_b32_e32 v49, v34
	v_mov_b32_e32 v66, v34
	v_mov_b32_e32 v67, v34
	v_mov_b32_e32 v68, v34
	v_mov_b32_e32 v69, v34
	v_mov_b32_e32 v70, v34
	v_mov_b32_e32 v71, v34
	v_mov_b32_e32 v72, v34
	v_mov_b32_e32 v73, v34
	v_mov_b32_e32 v74, v34
	v_mov_b32_e32 v75, v34
	v_mov_b32_e32 v76, v34
	v_mov_b32_e32 v77, v34
	v_mov_b32_e32 v78, v34
	v_mov_b32_e32 v79, v34
	v_mov_b32_e32 v80, v34
	v_mov_b32_e32 v81, v34
